# gate/up SwiGLU epilogue rewritten: one LDS burst for the 8 row scales, interleaved row reductions, 8 independent silu chains per row emitted stage by stage (f32 math unchanged)
# speedup vs baseline: 1.0219x; 1.0080x over previous
; __device__ __forceinline__ unsigned cvt_pk_bf16(float lo, float hi) { unsigned r; asm volatile("v_cvt_pk_bf16_f32 %0, %1, %2" : "=v"(r) : "v"(lo), "v"(hi)); return r; }
; #define LAS __attribute__((address_space(3)))
; __device__ __forceinline__ float fast_sigmoid(float x) { return __builtin_amdgcn_rcpf(1.0f + __expf(-x)); }
;     __device__ __forceinline__ void operator()(const f32x4 (&acc)[2][2][4][2], const pg8::Unit& u, int wr, int wc, int fr_, int fq_, LAS const unsigned char* xl) const {
;     ...
;         if (MODE == 0 || MODE == 1 || MODE == 4) {
; #pragma unroll
;             for (int ai = 0; ai < 2; ++ai)
; #pragma unroll
;                 for (int m = 0; m < 4; ++m) { const f32x4 pv = *(LAS const f32x4*)(xl + (ai * 128 + wr * 64 + m * 16 + fr) * 64 + fq * 16); rv[ai][m] = (pv[0] + pv[1]) + (pv[2] + pv[3]); }
; #pragma unroll
;             for (int ai = 0; ai < 2; ++ai)
; #pragma unroll
;                 for (int m = 0; m < 4; ++m) rv[ai][m] = __builtin_amdgcn_rsqf(xrow16_sum(rv[ai][m]) * (1.0f / 1024.0f) + EPS);
;     ...
;                         bf16_t* rowp = O + (size_t)row * ldc + u.pn * 128 + wc * 32 + 8 * fq;
;                         float a[8];
; #pragma unroll
;                         for (int n = 0; n < 2; ++n)
; #pragma unroll
;                             for (int j = 0; j < 4; ++j) { const float g = acc[ai][0][m][n][j] * rinv, up = acc[ai][1][m][n][j] * rinv; a[4 * n + j] = g * fast_sigmoid(g) * up; }
;                         u32x4 w; w.x = pg8::cvt_pk_bf16(a[0], a[1]); w.y = pg8::cvt_pk_bf16(a[2], a[3]); w.z = pg8::cvt_pk_bf16(a[4], a[5]); w.w = pg8::cvt_pk_bf16(a[6], a[7]);
;                         *(u32x4*)rowp = w;
.LBB0_425:
	s_and_b64 vcc, exec, s[6:7]
	v_add_u32_e32 v135, s48, v237
	v_lshlrev_b32_e32 v128, 4, v238
	v_lshlrev_b32_e32 v129, 6, v135
	s_mov_b32 s1, 0x20000
	v_add3_u32 v132, s1, v128, v129
	ds_read_b128 v[152:155], v132
	ds_read_b128 v[156:159], v132 offset:1024
	ds_read_b128 v[160:163], v132 offset:2048
	ds_read_b128 v[164:167], v132 offset:3072
	ds_read_b128 v[168:171], v132 offset:8192
	ds_read_b128 v[172:175], v132 offset:9216
	ds_read_b128 v[176:179], v132 offset:10240
	ds_read_b128 v[180:183], v132 offset:11264
	v_lshl_add_u32 v129, s0, 8, v135
	v_mov_b64_e32 v[130:131], s[72:73]
	s_lshl_b32 s0, s2, 7
	v_mad_i64_i32 v[148:149], s[26:27], v129, s83, v[130:131]
	s_ashr_i32 s1, s0, 31
	s_lshl_b64 s[0:1], s[0:1], 1
	v_lshlrev_b32_e32 v146, 3, v238
	v_ashrrev_i32_e32 v147, 31, v146
	v_lshl_add_u64 v[148:149], v[148:149], 0, s[0:1]
	v_lshl_add_u64 v[148:149], v[148:149], 0, s[86:87]
	v_lshlrev_b64 v[146:147], 1, v[146:147]
	v_lshl_add_u64 v[148:149], v[148:149], 0, v[146:147]
	s_mov_b32 s100, 0x18000
	s_mov_b32 s101, 0
	s_mov_b32 s0, 0x78000
	s_mov_b32 s1, 0
	s_waitcnt lgkmcnt(0)
	v_add_f32_e32 v152, v152, v153
	v_add_f32_e32 v154, v154, v155
	v_add_f32_e32 v156, v156, v157
	v_add_f32_e32 v158, v158, v159
	v_add_f32_e32 v160, v160, v161
	v_add_f32_e32 v162, v162, v163
	v_add_f32_e32 v164, v164, v165
	v_add_f32_e32 v166, v166, v167
	v_add_f32_e32 v168, v168, v169
	v_add_f32_e32 v170, v170, v171
	v_add_f32_e32 v172, v172, v173
	v_add_f32_e32 v174, v174, v175
	v_add_f32_e32 v176, v176, v177
	v_add_f32_e32 v178, v178, v179
	v_add_f32_e32 v180, v180, v181
	v_add_f32_e32 v182, v182, v183
	v_add_f32_e32 v184, v152, v154
	v_add_f32_e32 v185, v156, v158
	v_add_f32_e32 v186, v160, v162
	v_add_f32_e32 v187, v164, v166
	v_add_f32_e32 v188, v168, v170
	v_add_f32_e32 v189, v172, v174
	v_add_f32_e32 v190, v176, v178
	v_add_f32_e32 v191, v180, v182
	v_mov_b32_e32 v152, v184
	v_mov_b32_e32 v153, v185
	v_mov_b32_e32 v154, v186
	v_mov_b32_e32 v155, v187
	v_mov_b32_e32 v156, v188
	v_mov_b32_e32 v157, v189
	v_mov_b32_e32 v158, v190
	v_mov_b32_e32 v159, v191
	v_permlane16_swap_b32_e32 v184, v152
	v_permlane16_swap_b32_e32 v185, v153
	v_permlane16_swap_b32_e32 v186, v154
	v_permlane16_swap_b32_e32 v187, v155
	v_permlane16_swap_b32_e32 v188, v156
	v_permlane16_swap_b32_e32 v189, v157
	v_permlane16_swap_b32_e32 v190, v158
	v_permlane16_swap_b32_e32 v191, v159
	v_add_f32_e32 v184, v184, v152
	v_add_f32_e32 v185, v185, v153
	v_add_f32_e32 v186, v186, v154
	v_add_f32_e32 v187, v187, v155
	v_add_f32_e32 v188, v188, v156
	v_add_f32_e32 v189, v189, v157
	v_add_f32_e32 v190, v190, v158
	v_add_f32_e32 v191, v191, v159
	v_mov_b32_e32 v152, v184
	v_mov_b32_e32 v153, v185
	v_mov_b32_e32 v154, v186
	v_mov_b32_e32 v155, v187
	v_mov_b32_e32 v156, v188
	v_mov_b32_e32 v157, v189
	v_mov_b32_e32 v158, v190
	v_mov_b32_e32 v159, v191
	v_permlane32_swap_b32_e32 v184, v152
	v_permlane32_swap_b32_e32 v185, v153
	v_permlane32_swap_b32_e32 v186, v154
	v_permlane32_swap_b32_e32 v187, v155
	v_permlane32_swap_b32_e32 v188, v156
	v_permlane32_swap_b32_e32 v189, v157
	v_permlane32_swap_b32_e32 v190, v158
	v_permlane32_swap_b32_e32 v191, v159
	v_add_f32_e32 v184, v184, v152
	v_add_f32_e32 v185, v185, v153
	v_add_f32_e32 v186, v186, v154
	v_add_f32_e32 v187, v187, v155
	v_add_f32_e32 v188, v188, v156
	v_add_f32_e32 v189, v189, v157
	v_add_f32_e32 v190, v190, v158
	v_add_f32_e32 v191, v191, v159
	v_fmamk_f32 v184, v184, 0x3a800000, v233
	v_fmamk_f32 v185, v185, 0x3a800000, v233
	v_fmamk_f32 v186, v186, 0x3a800000, v233
	v_fmamk_f32 v187, v187, 0x3a800000, v233
	v_fmamk_f32 v188, v188, 0x3a800000, v233
	v_fmamk_f32 v189, v189, 0x3a800000, v233
	v_fmamk_f32 v190, v190, 0x3a800000, v233
	v_fmamk_f32 v191, v191, 0x3a800000, v233
	v_rsq_f32_e32 v184, v184
	v_rsq_f32_e32 v185, v185
	v_rsq_f32_e32 v186, v186
	v_rsq_f32_e32 v187, v187
	v_rsq_f32_e32 v188, v188
	v_rsq_f32_e32 v189, v189
	v_rsq_f32_e32 v190, v190
	v_rsq_f32_e32 v191, v191
	v_mul_f32_e32 v152, 0xbfb8aa3b, v184
	v_mul_f32_e32 v156, 0xbfb8aa3b, v185
	v_mul_f32_e32 v160, 0xbfb8aa3b, v186
	v_mul_f32_e32 v164, 0xbfb8aa3b, v187
	v_mul_f32_e32 v168, 0xbfb8aa3b, v188
	v_mul_f32_e32 v172, 0xbfb8aa3b, v189
	v_mul_f32_e32 v176, 0xbfb8aa3b, v190
	v_mul_f32_e32 v180, 0xbfb8aa3b, v191
	v_mul_f32_e32 v154, v184, v184
	v_mul_f32_e32 v158, v185, v185
	v_mul_f32_e32 v162, v186, v186
	v_mul_f32_e32 v166, v187, v187
	v_mul_f32_e32 v170, v188, v188
	v_mul_f32_e32 v174, v189, v189
	v_mul_f32_e32 v178, v190, v190
	v_mul_f32_e32 v182, v191, v191
	v_pk_mul_f32 v[124:125], v[120:121], v[124:125]
	v_pk_mul_f32 v[126:127], v[122:123], v[126:127]
	v_pk_mul_f32 v[116:117], v[112:113], v[116:117]
	v_pk_mul_f32 v[118:119], v[114:115], v[118:119]
	v_pk_mul_f32 v[120:121], v[120:121], v[152:153] op_sel_hi:[1,0]
	v_pk_mul_f32 v[122:123], v[122:123], v[152:153] op_sel_hi:[1,0]
	v_pk_mul_f32 v[112:113], v[112:113], v[152:153] op_sel_hi:[1,0]
	v_pk_mul_f32 v[114:115], v[114:115], v[152:153] op_sel_hi:[1,0]
	v_exp_f32_e32 v120, v120
	v_exp_f32_e32 v121, v121
	v_exp_f32_e32 v122, v122
	v_exp_f32_e32 v123, v123
	v_exp_f32_e32 v112, v112
	v_exp_f32_e32 v113, v113
	v_exp_f32_e32 v114, v114
	v_exp_f32_e32 v115, v115
	v_add_f32_e32 v120, 1.0, v120
	v_add_f32_e32 v121, 1.0, v121
	v_add_f32_e32 v122, 1.0, v122
	v_add_f32_e32 v123, 1.0, v123
	v_add_f32_e32 v112, 1.0, v112
	v_add_f32_e32 v113, 1.0, v113
	v_add_f32_e32 v114, 1.0, v114
	v_add_f32_e32 v115, 1.0, v115
	v_rcp_f32_e32 v120, v120
	v_rcp_f32_e32 v121, v121
	v_rcp_f32_e32 v122, v122
	v_rcp_f32_e32 v123, v123
	v_rcp_f32_e32 v112, v112
	v_rcp_f32_e32 v113, v113
	v_rcp_f32_e32 v114, v114
	v_rcp_f32_e32 v115, v115
; __device__ __forceinline__ unsigned cvt_pk_bf16(float lo, float hi) { unsigned r; asm volatile("v_cvt_pk_bf16_f32 %0, %1, %2" : "=v"(r) : "v"(lo), "v"(hi)); return r; }
; __device__ __forceinline__ float fast_sigmoid(float x) { return __builtin_amdgcn_rcpf(1.0f + __expf(-x)); }
;     __device__ __forceinline__ void operator()(const f32x4 (&acc)[2][2][4][2], const pg8::Unit& u, int wr, int wc, int fr_, int fq_, LAS const unsigned char* xl) const {
;     ...
;                     } else {
;                         bf16_t* rowp = O + (size_t)row * ldc + u.pn * 128 + wc * 32 + 8 * fq;
;                         float a[8];
; #pragma unroll
;                         for (int n = 0; n < 2; ++n)
; #pragma unroll
;                             for (int j = 0; j < 4; ++j) { const float g = acc[ai][0][m][n][j] * rinv, up = acc[ai][1][m][n][j] * rinv; a[4 * n + j] = g * fast_sigmoid(g) * up; }
;                         u32x4 w; w.x = pg8::cvt_pk_bf16(a[0], a[1]); w.y = pg8::cvt_pk_bf16(a[2], a[3]); w.z = pg8::cvt_pk_bf16(a[4], a[5]); w.w = pg8::cvt_pk_bf16(a[6], a[7]);
;                         *(u32x4*)rowp = w;
	v_pk_mul_f32 v[124:125], v[124:125], v[154:155] op_sel_hi:[1,0]
	v_pk_mul_f32 v[126:127], v[126:127], v[154:155] op_sel_hi:[1,0]
	v_pk_mul_f32 v[116:117], v[116:117], v[154:155] op_sel_hi:[1,0]
	v_pk_mul_f32 v[118:119], v[118:119], v[154:155] op_sel_hi:[1,0]
	v_lshl_add_u64 v[150:151], v[148:149], 0, s[100:101]
	v_pk_mul_f32 v[124:125], v[124:125], v[120:121]
	v_pk_mul_f32 v[126:127], v[126:127], v[122:123]
	v_pk_mul_f32 v[116:117], v[116:117], v[112:113]
	v_pk_mul_f32 v[118:119], v[118:119], v[114:115]
	s_nop 0
	v_cvt_pk_bf16_f32 v136, v124, v125
	v_cvt_pk_bf16_f32 v137, v126, v127
	v_cvt_pk_bf16_f32 v138, v116, v117
	v_cvt_pk_bf16_f32 v139, v118, v119
	global_store_dwordx4 v[148:149], v[136:139], off
	v_pk_mul_f32 v[108:109], v[104:105], v[108:109]
	v_pk_mul_f32 v[110:111], v[106:107], v[110:111]
	v_pk_mul_f32 v[100:101], v[96:97], v[100:101]
	v_pk_mul_f32 v[102:103], v[98:99], v[102:103]
	v_pk_mul_f32 v[104:105], v[104:105], v[156:157] op_sel_hi:[1,0]
	v_pk_mul_f32 v[106:107], v[106:107], v[156:157] op_sel_hi:[1,0]
	v_pk_mul_f32 v[96:97], v[96:97], v[156:157] op_sel_hi:[1,0]
	v_pk_mul_f32 v[98:99], v[98:99], v[156:157] op_sel_hi:[1,0]
	v_exp_f32_e32 v104, v104
	v_exp_f32_e32 v105, v105
	v_exp_f32_e32 v106, v106
	v_exp_f32_e32 v107, v107
	v_exp_f32_e32 v96, v96
	v_exp_f32_e32 v97, v97
	v_exp_f32_e32 v98, v98
	v_exp_f32_e32 v99, v99
	v_add_f32_e32 v104, 1.0, v104
	v_add_f32_e32 v105, 1.0, v105
	v_add_f32_e32 v106, 1.0, v106
	v_add_f32_e32 v107, 1.0, v107
	v_add_f32_e32 v96, 1.0, v96
	v_add_f32_e32 v97, 1.0, v97
	v_add_f32_e32 v98, 1.0, v98
	v_add_f32_e32 v99, 1.0, v99
	v_rcp_f32_e32 v104, v104
	v_rcp_f32_e32 v105, v105
	v_rcp_f32_e32 v106, v106
	v_rcp_f32_e32 v107, v107
	v_rcp_f32_e32 v96, v96
	v_rcp_f32_e32 v97, v97
	v_rcp_f32_e32 v98, v98
	v_rcp_f32_e32 v99, v99
	v_pk_mul_f32 v[108:109], v[108:109], v[158:159] op_sel_hi:[1,0]
	v_pk_mul_f32 v[110:111], v[110:111], v[158:159] op_sel_hi:[1,0]
	v_pk_mul_f32 v[100:101], v[100:101], v[158:159] op_sel_hi:[1,0]
	v_pk_mul_f32 v[102:103], v[102:103], v[158:159] op_sel_hi:[1,0]
	v_lshl_add_u64 v[148:149], v[150:151], 0, s[100:101]
	v_pk_mul_f32 v[108:109], v[108:109], v[104:105]
	v_pk_mul_f32 v[110:111], v[110:111], v[106:107]
	v_pk_mul_f32 v[100:101], v[100:101], v[96:97]
	v_pk_mul_f32 v[102:103], v[102:103], v[98:99]
	s_nop 0
	v_cvt_pk_bf16_f32 v140, v108, v109
	v_cvt_pk_bf16_f32 v141, v110, v111
	v_cvt_pk_bf16_f32 v142, v100, v101
	v_cvt_pk_bf16_f32 v143, v102, v103
	global_store_dwordx4 v[150:151], v[140:143], off
	v_pk_mul_f32 v[92:93], v[88:89], v[92:93]
	v_pk_mul_f32 v[94:95], v[90:91], v[94:95]
	v_pk_mul_f32 v[84:85], v[80:81], v[84:85]
	v_pk_mul_f32 v[86:87], v[82:83], v[86:87]
	v_pk_mul_f32 v[88:89], v[88:89], v[160:161] op_sel_hi:[1,0]
	v_pk_mul_f32 v[90:91], v[90:91], v[160:161] op_sel_hi:[1,0]
	v_pk_mul_f32 v[80:81], v[80:81], v[160:161] op_sel_hi:[1,0]
	v_pk_mul_f32 v[82:83], v[82:83], v[160:161] op_sel_hi:[1,0]
	v_exp_f32_e32 v88, v88
	v_exp_f32_e32 v89, v89
	v_exp_f32_e32 v90, v90
	v_exp_f32_e32 v91, v91
	v_exp_f32_e32 v80, v80
	v_exp_f32_e32 v81, v81
	v_exp_f32_e32 v82, v82
	v_exp_f32_e32 v83, v83
	v_add_f32_e32 v88, 1.0, v88
	v_add_f32_e32 v89, 1.0, v89
	v_add_f32_e32 v90, 1.0, v90
	v_add_f32_e32 v91, 1.0, v91
	v_add_f32_e32 v80, 1.0, v80
	v_add_f32_e32 v81, 1.0, v81
	v_add_f32_e32 v82, 1.0, v82
	v_add_f32_e32 v83, 1.0, v83
	v_rcp_f32_e32 v88, v88
	v_rcp_f32_e32 v89, v89
	v_rcp_f32_e32 v90, v90
	v_rcp_f32_e32 v91, v91
	v_rcp_f32_e32 v80, v80
	v_rcp_f32_e32 v81, v81
	v_rcp_f32_e32 v82, v82
	v_rcp_f32_e32 v83, v83
	v_pk_mul_f32 v[92:93], v[92:93], v[162:163] op_sel_hi:[1,0]
	v_pk_mul_f32 v[94:95], v[94:95], v[162:163] op_sel_hi:[1,0]
	v_pk_mul_f32 v[84:85], v[84:85], v[162:163] op_sel_hi:[1,0]
	v_pk_mul_f32 v[86:87], v[86:87], v[162:163] op_sel_hi:[1,0]
	v_lshl_add_u64 v[150:151], v[148:149], 0, s[100:101]
	v_pk_mul_f32 v[92:93], v[92:93], v[88:89]
	v_pk_mul_f32 v[94:95], v[94:95], v[90:91]
	v_pk_mul_f32 v[84:85], v[84:85], v[80:81]
	v_pk_mul_f32 v[86:87], v[86:87], v[82:83]
	s_nop 0
	v_cvt_pk_bf16_f32 v136, v92, v93
	v_cvt_pk_bf16_f32 v137, v94, v95
	v_cvt_pk_bf16_f32 v138, v84, v85
	v_cvt_pk_bf16_f32 v139, v86, v87
	global_store_dwordx4 v[148:149], v[136:139], off
	v_pk_mul_f32 v[76:77], v[72:73], v[76:77]
	v_pk_mul_f32 v[78:79], v[74:75], v[78:79]
	v_pk_mul_f32 v[68:69], v[64:65], v[68:69]
	v_pk_mul_f32 v[70:71], v[66:67], v[70:71]
	v_pk_mul_f32 v[72:73], v[72:73], v[164:165] op_sel_hi:[1,0]
	v_pk_mul_f32 v[74:75], v[74:75], v[164:165] op_sel_hi:[1,0]
	v_pk_mul_f32 v[64:65], v[64:65], v[164:165] op_sel_hi:[1,0]
	v_pk_mul_f32 v[66:67], v[66:67], v[164:165] op_sel_hi:[1,0]
	v_exp_f32_e32 v72, v72
	v_exp_f32_e32 v73, v73
	v_exp_f32_e32 v74, v74
	v_exp_f32_e32 v75, v75
	v_exp_f32_e32 v64, v64
	v_exp_f32_e32 v65, v65
	v_exp_f32_e32 v66, v66
	v_exp_f32_e32 v67, v67
	v_add_f32_e32 v72, 1.0, v72
	v_add_f32_e32 v73, 1.0, v73
	v_add_f32_e32 v74, 1.0, v74
	v_add_f32_e32 v75, 1.0, v75
	v_add_f32_e32 v64, 1.0, v64
	v_add_f32_e32 v65, 1.0, v65
	v_add_f32_e32 v66, 1.0, v66
	v_add_f32_e32 v67, 1.0, v67
	v_rcp_f32_e32 v72, v72
	v_rcp_f32_e32 v73, v73
	v_rcp_f32_e32 v74, v74
	v_rcp_f32_e32 v75, v75
	v_rcp_f32_e32 v64, v64
	v_rcp_f32_e32 v65, v65
	v_rcp_f32_e32 v66, v66
	v_rcp_f32_e32 v67, v67
	v_pk_mul_f32 v[76:77], v[76:77], v[166:167] op_sel_hi:[1,0]
	v_pk_mul_f32 v[78:79], v[78:79], v[166:167] op_sel_hi:[1,0]
	v_pk_mul_f32 v[68:69], v[68:69], v[166:167] op_sel_hi:[1,0]
	v_pk_mul_f32 v[70:71], v[70:71], v[166:167] op_sel_hi:[1,0]
	v_lshl_add_u64 v[148:149], v[150:151], 0, s[0:1]
	v_pk_mul_f32 v[76:77], v[76:77], v[72:73]
	v_pk_mul_f32 v[78:79], v[78:79], v[74:75]
	v_pk_mul_f32 v[68:69], v[68:69], v[64:65]
; __device__ __forceinline__ unsigned cvt_pk_bf16(float lo, float hi) { unsigned r; asm volatile("v_cvt_pk_bf16_f32 %0, %1, %2" : "=v"(r) : "v"(lo), "v"(hi)); return r; }
; __device__ __forceinline__ float fast_sigmoid(float x) { return __builtin_amdgcn_rcpf(1.0f + __expf(-x)); }
;     __device__ __forceinline__ void operator()(const f32x4 (&acc)[2][2][4][2], const pg8::Unit& u, int wr, int wc, int fr_, int fq_, LAS const unsigned char* xl) const {
;     ...
;                     } else {
;                         bf16_t* rowp = O + (size_t)row * ldc + u.pn * 128 + wc * 32 + 8 * fq;
;                         float a[8];
; #pragma unroll
;                         for (int n = 0; n < 2; ++n)
; #pragma unroll
;                             for (int j = 0; j < 4; ++j) { const float g = acc[ai][0][m][n][j] * rinv, up = acc[ai][1][m][n][j] * rinv; a[4 * n + j] = g * fast_sigmoid(g) * up; }
;                         u32x4 w; w.x = pg8::cvt_pk_bf16(a[0], a[1]); w.y = pg8::cvt_pk_bf16(a[2], a[3]); w.z = pg8::cvt_pk_bf16(a[4], a[5]); w.w = pg8::cvt_pk_bf16(a[6], a[7]);
;                         *(u32x4*)rowp = w;
	v_pk_mul_f32 v[70:71], v[70:71], v[66:67]
	s_nop 0
	v_cvt_pk_bf16_f32 v140, v76, v77
	v_cvt_pk_bf16_f32 v141, v78, v79
	v_cvt_pk_bf16_f32 v142, v68, v69
	v_cvt_pk_bf16_f32 v143, v70, v71
	global_store_dwordx4 v[150:151], v[140:143], off
	v_pk_mul_f32 v[60:61], v[56:57], v[60:61]
	v_pk_mul_f32 v[62:63], v[58:59], v[62:63]
	v_pk_mul_f32 v[52:53], v[48:49], v[52:53]
	v_pk_mul_f32 v[54:55], v[50:51], v[54:55]
	v_pk_mul_f32 v[56:57], v[56:57], v[168:169] op_sel_hi:[1,0]
	v_pk_mul_f32 v[58:59], v[58:59], v[168:169] op_sel_hi:[1,0]
	v_pk_mul_f32 v[48:49], v[48:49], v[168:169] op_sel_hi:[1,0]
	v_pk_mul_f32 v[50:51], v[50:51], v[168:169] op_sel_hi:[1,0]
	v_exp_f32_e32 v56, v56
	v_exp_f32_e32 v57, v57
	v_exp_f32_e32 v58, v58
	v_exp_f32_e32 v59, v59
	v_exp_f32_e32 v48, v48
	v_exp_f32_e32 v49, v49
	v_exp_f32_e32 v50, v50
	v_exp_f32_e32 v51, v51
	v_add_f32_e32 v56, 1.0, v56
	v_add_f32_e32 v57, 1.0, v57
	v_add_f32_e32 v58, 1.0, v58
	v_add_f32_e32 v59, 1.0, v59
	v_add_f32_e32 v48, 1.0, v48
	v_add_f32_e32 v49, 1.0, v49
	v_add_f32_e32 v50, 1.0, v50
	v_add_f32_e32 v51, 1.0, v51
	v_rcp_f32_e32 v56, v56
	v_rcp_f32_e32 v57, v57
	v_rcp_f32_e32 v58, v58
	v_rcp_f32_e32 v59, v59
	v_rcp_f32_e32 v48, v48
	v_rcp_f32_e32 v49, v49
	v_rcp_f32_e32 v50, v50
	v_rcp_f32_e32 v51, v51
	v_pk_mul_f32 v[60:61], v[60:61], v[170:171] op_sel_hi:[1,0]
	v_pk_mul_f32 v[62:63], v[62:63], v[170:171] op_sel_hi:[1,0]
	v_pk_mul_f32 v[52:53], v[52:53], v[170:171] op_sel_hi:[1,0]
	v_pk_mul_f32 v[54:55], v[54:55], v[170:171] op_sel_hi:[1,0]
	v_lshl_add_u64 v[150:151], v[148:149], 0, s[100:101]
	v_pk_mul_f32 v[60:61], v[60:61], v[56:57]
	v_pk_mul_f32 v[62:63], v[62:63], v[58:59]
	v_pk_mul_f32 v[52:53], v[52:53], v[48:49]
	v_pk_mul_f32 v[54:55], v[54:55], v[50:51]
	s_nop 0
	v_cvt_pk_bf16_f32 v136, v60, v61
	v_cvt_pk_bf16_f32 v137, v62, v63
	v_cvt_pk_bf16_f32 v138, v52, v53
	v_cvt_pk_bf16_f32 v139, v54, v55
	global_store_dwordx4 v[148:149], v[136:139], off
	v_pk_mul_f32 v[44:45], v[40:41], v[44:45]
	v_pk_mul_f32 v[46:47], v[42:43], v[46:47]
	v_pk_mul_f32 v[36:37], v[32:33], v[36:37]
	v_pk_mul_f32 v[38:39], v[34:35], v[38:39]
	v_pk_mul_f32 v[40:41], v[40:41], v[172:173] op_sel_hi:[1,0]
	v_pk_mul_f32 v[42:43], v[42:43], v[172:173] op_sel_hi:[1,0]
	v_pk_mul_f32 v[32:33], v[32:33], v[172:173] op_sel_hi:[1,0]
	v_pk_mul_f32 v[34:35], v[34:35], v[172:173] op_sel_hi:[1,0]
	v_exp_f32_e32 v40, v40
	v_exp_f32_e32 v41, v41
	v_exp_f32_e32 v42, v42
	v_exp_f32_e32 v43, v43
	v_exp_f32_e32 v32, v32
	v_exp_f32_e32 v33, v33
	v_exp_f32_e32 v34, v34
	v_exp_f32_e32 v35, v35
	v_add_f32_e32 v40, 1.0, v40
	v_add_f32_e32 v41, 1.0, v41
	v_add_f32_e32 v42, 1.0, v42
	v_add_f32_e32 v43, 1.0, v43
	v_add_f32_e32 v32, 1.0, v32
	v_add_f32_e32 v33, 1.0, v33
	v_add_f32_e32 v34, 1.0, v34
	v_add_f32_e32 v35, 1.0, v35
	v_rcp_f32_e32 v40, v40
	v_rcp_f32_e32 v41, v41
	v_rcp_f32_e32 v42, v42
	v_rcp_f32_e32 v43, v43
	v_rcp_f32_e32 v32, v32
	v_rcp_f32_e32 v33, v33
	v_rcp_f32_e32 v34, v34
	v_rcp_f32_e32 v35, v35
	v_pk_mul_f32 v[44:45], v[44:45], v[174:175] op_sel_hi:[1,0]
	v_pk_mul_f32 v[46:47], v[46:47], v[174:175] op_sel_hi:[1,0]
	v_pk_mul_f32 v[36:37], v[36:37], v[174:175] op_sel_hi:[1,0]
	v_pk_mul_f32 v[38:39], v[38:39], v[174:175] op_sel_hi:[1,0]
	v_lshl_add_u64 v[148:149], v[150:151], 0, s[100:101]
	v_pk_mul_f32 v[44:45], v[44:45], v[40:41]
	v_pk_mul_f32 v[46:47], v[46:47], v[42:43]
	v_pk_mul_f32 v[36:37], v[36:37], v[32:33]
	v_pk_mul_f32 v[38:39], v[38:39], v[34:35]
	s_nop 0
	v_cvt_pk_bf16_f32 v140, v44, v45
	v_cvt_pk_bf16_f32 v141, v46, v47
	v_cvt_pk_bf16_f32 v142, v36, v37
	v_cvt_pk_bf16_f32 v143, v38, v39
	global_store_dwordx4 v[150:151], v[140:143], off
	v_pk_mul_f32 v[28:29], v[24:25], v[28:29]
	v_pk_mul_f32 v[30:31], v[26:27], v[30:31]
	v_pk_mul_f32 v[20:21], v[16:17], v[20:21]
	v_pk_mul_f32 v[22:23], v[18:19], v[22:23]
	v_pk_mul_f32 v[24:25], v[24:25], v[176:177] op_sel_hi:[1,0]
	v_pk_mul_f32 v[26:27], v[26:27], v[176:177] op_sel_hi:[1,0]
	v_pk_mul_f32 v[16:17], v[16:17], v[176:177] op_sel_hi:[1,0]
	v_pk_mul_f32 v[18:19], v[18:19], v[176:177] op_sel_hi:[1,0]
	v_exp_f32_e32 v24, v24
	v_exp_f32_e32 v25, v25
	v_exp_f32_e32 v26, v26
	v_exp_f32_e32 v27, v27
	v_exp_f32_e32 v16, v16
	v_exp_f32_e32 v17, v17
	v_exp_f32_e32 v18, v18
	v_exp_f32_e32 v19, v19
	v_add_f32_e32 v24, 1.0, v24
	v_add_f32_e32 v25, 1.0, v25
	v_add_f32_e32 v26, 1.0, v26
	v_add_f32_e32 v27, 1.0, v27
	v_add_f32_e32 v16, 1.0, v16
	v_add_f32_e32 v17, 1.0, v17
	v_add_f32_e32 v18, 1.0, v18
	v_add_f32_e32 v19, 1.0, v19
	v_rcp_f32_e32 v24, v24
	v_rcp_f32_e32 v25, v25
	v_rcp_f32_e32 v26, v26
	v_rcp_f32_e32 v27, v27
	v_rcp_f32_e32 v16, v16
	v_rcp_f32_e32 v17, v17
	v_rcp_f32_e32 v18, v18
	v_rcp_f32_e32 v19, v19
	v_pk_mul_f32 v[28:29], v[28:29], v[178:179] op_sel_hi:[1,0]
	v_pk_mul_f32 v[30:31], v[30:31], v[178:179] op_sel_hi:[1,0]
	v_pk_mul_f32 v[20:21], v[20:21], v[178:179] op_sel_hi:[1,0]
	v_pk_mul_f32 v[22:23], v[22:23], v[178:179] op_sel_hi:[1,0]
	v_lshl_add_u64 v[150:151], v[148:149], 0, s[100:101]
	v_pk_mul_f32 v[28:29], v[28:29], v[24:25]
	v_pk_mul_f32 v[30:31], v[30:31], v[26:27]
	v_pk_mul_f32 v[20:21], v[20:21], v[16:17]
	v_pk_mul_f32 v[22:23], v[22:23], v[18:19]
	s_nop 0
	v_cvt_pk_bf16_f32 v136, v28, v29
	v_cvt_pk_bf16_f32 v137, v30, v31
	v_cvt_pk_bf16_f32 v138, v20, v21
	v_cvt_pk_bf16_f32 v139, v22, v23
	global_store_dwordx4 v[148:149], v[136:139], off
	v_pk_mul_f32 v[12:13], v[8:9], v[12:13]
	v_pk_mul_f32 v[14:15], v[10:11], v[14:15]
	v_pk_mul_f32 v[0:1], v[4:5], v[0:1]
	v_pk_mul_f32 v[2:3], v[6:7], v[2:3]
	v_pk_mul_f32 v[8:9], v[8:9], v[180:181] op_sel_hi:[1,0]
	v_pk_mul_f32 v[10:11], v[10:11], v[180:181] op_sel_hi:[1,0]
	v_pk_mul_f32 v[4:5], v[4:5], v[180:181] op_sel_hi:[1,0]
	v_pk_mul_f32 v[6:7], v[6:7], v[180:181] op_sel_hi:[1,0]
	v_exp_f32_e32 v8, v8
	v_exp_f32_e32 v9, v9
	v_exp_f32_e32 v10, v10
	v_exp_f32_e32 v11, v11
	v_exp_f32_e32 v4, v4
	v_exp_f32_e32 v5, v5
	v_exp_f32_e32 v6, v6
	v_exp_f32_e32 v7, v7
	v_add_f32_e32 v8, 1.0, v8
	v_add_f32_e32 v9, 1.0, v9
	v_add_f32_e32 v10, 1.0, v10
	v_add_f32_e32 v11, 1.0, v11
	v_add_f32_e32 v4, 1.0, v4
	v_add_f32_e32 v5, 1.0, v5
	v_add_f32_e32 v6, 1.0, v6
	v_add_f32_e32 v7, 1.0, v7
	v_rcp_f32_e32 v8, v8
	v_rcp_f32_e32 v9, v9
	v_rcp_f32_e32 v10, v10
	v_rcp_f32_e32 v11, v11
	v_rcp_f32_e32 v4, v4
	v_rcp_f32_e32 v5, v5
	v_rcp_f32_e32 v6, v6
	v_rcp_f32_e32 v7, v7
	v_pk_mul_f32 v[12:13], v[12:13], v[182:183] op_sel_hi:[1,0]
	v_pk_mul_f32 v[14:15], v[14:15], v[182:183] op_sel_hi:[1,0]
	v_pk_mul_f32 v[0:1], v[0:1], v[182:183] op_sel_hi:[1,0]
	v_pk_mul_f32 v[2:3], v[2:3], v[182:183] op_sel_hi:[1,0]
	v_pk_mul_f32 v[12:13], v[12:13], v[8:9]
	v_pk_mul_f32 v[14:15], v[14:15], v[10:11]
	v_pk_mul_f32 v[0:1], v[0:1], v[4:5]
	v_pk_mul_f32 v[2:3], v[2:3], v[6:7]
	s_nop 0
	v_cvt_pk_bf16_f32 v140, v12, v13
	v_cvt_pk_bf16_f32 v141, v14, v15
	v_cvt_pk_bf16_f32 v142, v0, v1
	v_cvt_pk_bf16_f32 v143, v2, v3
	global_store_dwordx4 v[150:151], v[140:143], off
	s_mov_b64 s[0:1], -1
	s_cbranch_vccnz .LBB0_403
	s_andn2_b64 vcc, exec, s[20:21]
	s_cbranch_vccnz .LBB0_402
	s_barrier
	s_branch .LBB0_402
